# v15 + route_a: next unit's query fragments prefetched one unit ahead
# speedup vs baseline: 1.0076x; 1.0076x over previous
.LBB0_946:
	s_or_b64 exec, exec, s[0:1]
	s_add_u32 s6, s74, 0x2000000
	s_addc_u32 s7, s75, 0
	s_add_u32 s8, s74, 0x4000000
	s_addc_u32 s9, s75, 0
	v_readlane_b32 s0, v247, 0
	s_cmpk_gt_u32 s0, 0x1fff
	s_waitcnt lgkmcnt(0)
	s_barrier
	v_readlane_b32 s1, v247, 1
	s_cbranch_scc1 .LBB0_951
	v_readlane_b32 s12, v247, 2
	v_readlane_b32 s18, v247, 8
	s_lshr_b32 s12, s18, 1
	s_lshl_b32 s0, s2, 24
	s_add_u32 s4, s6, s0
	s_addc_u32 s5, s7, 0
	s_add_u32 s10, s8, s0
	v_readlane_b32 s0, v247, 0
	v_readlane_b32 s1, v247, 1
	v_readlane_b32 s13, v247, 3
	v_lshl_or_b32 v0, v129, 4, v80
	s_movk_i32 s1, 0x214
	v_mul_u32_u24_e32 v4, 0x214, v155
	v_mul_u32_u24_e32 v22, 0x84, v157
	v_readlane_b32 s14, v247, 4
	v_readlane_b32 s15, v247, 5
	v_readlane_b32 s16, v247, 6
	v_readlane_b32 s17, v247, 7
	s_addc_u32 s11, s9, 0
	s_lshr_b32 s13, s0, 1
	s_lshl_b32 s0, s2, 7
	v_mov_b32_e32 v1, 0
	v_lshlrev_b32_e32 v2, 1, v82
	v_mad_u32_u24 v0, v0, s1, v156
	v_add_u32_e32 v37, v4, v22
	s_mov_b32 s3, 0
	v_cmp_eq_u32_e32 vcc, 0, v157
	v_bfe_u32 v5, v130, 2, 4
	v_add3_u32 v6, v84, v158, v2
	v_or_b32_e32 v7, 1, v78
	v_or_b32_e32 v8, 2, v78
	v_or_b32_e32 v9, 3, v78
	v_or_b32_e32 v10, 4, v78
	v_or_b32_e32 v11, 5, v78
	v_or_b32_e32 v12, 6, v78
	v_or_b32_e32 v13, 7, v78
	v_or_b32_e32 v14, 8, v78
	v_or_b32_e32 v15, 9, v78
	v_or_b32_e32 v16, 10, v78
	v_or_b32_e32 v17, 11, v78
	v_or_b32_e32 v18, 12, v78
	v_or_b32_e32 v19, 13, v78
	v_or_b32_e32 v20, 14, v78
	v_or_b32_e32 v21, 15, v78
	s_lshl_b32 s14, s13, 2
	s_lshl_b32 s15, s12, 2
	s_lshl_b32 s16, s13, 3
	s_lshl_b32 s17, s12, 3
	s_lshl_b32 s2, s0, 1
	v_lshlrev_b32_e32 v2, 1, v82
	v_mov_b32_e32 v3, v1
	v_add_u32_e32 v22, 0x8800, v37
	v_add_u32_e32 v23, 0x8840, v37
	v_add_u32_e32 v24, 0x8808, v37
	v_add_u32_e32 v25, 0x8848, v37
	v_add_u32_e32 v26, 0x8810, v37
	v_add_u32_e32 v27, 0x8850, v37
	v_add_u32_e32 v28, 0x8818, v37
	v_add_u32_e32 v29, 0x8858, v37
	v_add_u32_e32 v30, 0x8820, v37
	v_add_u32_e32 v31, 0x8860, v37
	v_add_u32_e32 v32, 0x8828, v37
	v_add_u32_e32 v33, 0x8868, v37
	v_add_u32_e32 v34, 0x8830, v37
	v_add_u32_e32 v35, 0x8870, v37
	v_add_u32_e32 v36, 0x8838, v37
	v_add_u32_e32 v37, 0x8878, v37
	v_add_u32_e32 v38, 0x8800, v0
	v_add_u32_e32 v39, 0x8c00, v0
	v_add_u32_e32 v40, 0x8e00, v0
	v_readlane_b32 s19, v247, 9
	s_and_b32 s23, s16, 0x7ff0
	s_and_b32 s24, s14, 4
	v_mov_b32_e32 v141, 0
	v_or_b32_e32 v140, s23, v137
	v_add_u32_e32 v178, s24, v129
	v_lshlrev_b32_e32 v140, 12, v140
	v_lshl_add_u64 v[176:177], s[70:71], 0, v[140:141]
	v_lshlrev_b32_e32 v140, 9, v178
	v_lshl_add_u64 v[176:177], v[176:177], 0, v[140:141]
	v_lshl_add_u64 v[176:177], v[176:177], 0, s[2:3]
	v_lshl_add_u64 v[176:177], v[176:177], 0, v[2:3]
	global_load_dwordx4 v[160:163], v[176:177], off
	global_load_dwordx4 v[164:167], v[176:177], off offset:64
	global_load_dwordx4 v[168:171], v[176:177], off offset:128
	global_load_dwordx4 v[172:175], v[176:177], off offset:192
	s_waitcnt vmcnt(0)
	s_branch .LBB0_949

.LBB0_949:
	s_and_b32 s18, s16, 0x7ff0
	s_and_b32 s0, s14, 4
	v_or_b32_e32 v0, s18, v137
	v_add_u32_e32 v41, s0, v129
	v_lshlrev_b32_e32 v0, 12, v0
	v_lshl_add_u64 v[42:43], s[70:71], 0, v[0:1]
	v_lshlrev_b32_e32 v0, 9, v41
	v_lshl_add_u64 v[42:43], v[42:43], 0, v[0:1]
	v_lshl_add_u64 v[42:43], v[42:43], 0, s[2:3]
	v_lshl_add_u64 v[54:55], v[42:43], 0, v[2:3]
	s_waitcnt vmcnt(8)
	v_mov_b32_e32 v42, v160
	v_mov_b32_e32 v43, v161
	v_mov_b32_e32 v44, v162
	v_mov_b32_e32 v45, v163
	v_mov_b32_e32 v46, v164
	v_mov_b32_e32 v47, v165
	v_mov_b32_e32 v48, v166
	v_mov_b32_e32 v49, v167
	v_mov_b32_e32 v50, v168
	v_mov_b32_e32 v51, v169
	v_mov_b32_e32 v52, v170
	v_mov_b32_e32 v53, v171
	v_mov_b32_e32 v54, v172
	v_mov_b32_e32 v55, v173
	v_mov_b32_e32 v56, v174
	v_mov_b32_e32 v57, v175
	s_add_i32 s20, s16, s17
	s_add_i32 s22, s14, s15
	s_and_b32 s23, s20, 0x7ff0
	s_and_b32 s24, s22, 4
	v_mov_b32_e32 v141, 0
	v_or_b32_e32 v140, s23, v137
	v_add_u32_e32 v178, s24, v129
	v_lshlrev_b32_e32 v140, 12, v140
	v_lshl_add_u64 v[176:177], s[70:71], 0, v[140:141]
	v_lshlrev_b32_e32 v140, 9, v178
	v_lshl_add_u64 v[176:177], v[176:177], 0, v[140:141]
	v_lshl_add_u64 v[176:177], v[176:177], 0, s[2:3]
	v_lshl_add_u64 v[176:177], v[176:177], 0, v[2:3]
	global_load_dwordx4 v[160:163], v[176:177], off
	global_load_dwordx4 v[164:167], v[176:177], off offset:64
	global_load_dwordx4 v[168:171], v[176:177], off offset:128
	global_load_dwordx4 v[172:175], v[176:177], off offset:192
	s_barrier
	ds_read_b128 v[58:61], v6
	ds_read_b128 v[62:65], v6 offset:64
	ds_read_b128 v[66:69], v6 offset:4352
	ds_read_b128 v[84:87], v6 offset:4416
	ds_read_b128 v[88:91], v6 offset:8704
	ds_read_b128 v[92:95], v6 offset:8768
	ds_read_b128 v[96:99], v6 offset:13056
	ds_read_b128 v[100:103], v6 offset:13120
	ds_read_b128 v[104:107], v6 offset:17408
	ds_read_b128 v[108:111], v6 offset:17472
	ds_read_b128 v[112:115], v6 offset:21760
	ds_read_b128 v[116:119], v6 offset:21824
	ds_read_b128 v[120:123], v6 offset:26112
	ds_read_b128 v[124:127], v6 offset:26176
	s_waitcnt lgkmcnt(13)
	v_mfma_f32_16x16x32_bf16 v[58:61], v[42:45], v[58:61], 0
	s_waitcnt lgkmcnt(11)
	v_mfma_f32_16x16x32_bf16 v[66:69], v[42:45], v[66:69], 0
	s_waitcnt lgkmcnt(9)
	v_mfma_f32_16x16x32_bf16 v[88:91], v[42:45], v[88:91], 0
	s_waitcnt lgkmcnt(7)
	v_mfma_f32_16x16x32_bf16 v[96:99], v[42:45], v[96:99], 0
	s_waitcnt lgkmcnt(5)
	v_mfma_f32_16x16x32_bf16 v[104:107], v[42:45], v[104:107], 0
	v_mfma_f32_16x16x32_bf16 v[58:61], v[46:49], v[62:65], v[58:61]
	v_mfma_f32_16x16x32_bf16 v[62:65], v[46:49], v[84:87], v[66:69]
	v_mfma_f32_16x16x32_bf16 v[66:69], v[46:49], v[92:95], v[88:91]
	v_mfma_f32_16x16x32_bf16 v[84:87], v[46:49], v[100:103], v[96:99]
	s_waitcnt lgkmcnt(4)
	v_mfma_f32_16x16x32_bf16 v[88:91], v[46:49], v[108:111], v[104:107]
	ds_read_b128 v[100:103], v6 offset:128
	s_nop 1
	ds_read_b128 v[104:107], v6 offset:192
	s_waitcnt lgkmcnt(5)
	v_mfma_f32_16x16x32_bf16 v[112:115], v[42:45], v[112:115], 0
	s_waitcnt lgkmcnt(1)
	v_mfma_f32_16x16x32_bf16 v[58:61], v[50:53], v[100:103], v[58:61]
	ds_read_b128 v[100:103], v6 offset:4480
	ds_read_b128 v[108:111], v6 offset:4544
	v_mfma_f32_16x16x32_bf16 v[92:95], v[46:49], v[116:119], v[112:115]
	s_waitcnt lgkmcnt(1)
	v_mfma_f32_16x16x32_bf16 v[62:65], v[50:53], v[100:103], v[62:65]
	ds_read_b128 v[100:103], v6 offset:8832
	ds_read_b128 v[112:115], v6 offset:8896
	v_mfma_f32_16x16x32_bf16 v[120:123], v[42:45], v[120:123], 0
	s_waitcnt lgkmcnt(1)
	v_mfma_f32_16x16x32_bf16 v[66:69], v[50:53], v[100:103], v[66:69]
	ds_read_b128 v[100:103], v6 offset:13184
	ds_read_b128 v[116:119], v6 offset:13248
	v_mfma_f32_16x16x32_bf16 v[96:99], v[46:49], v[124:127], v[120:123]
	s_waitcnt lgkmcnt(1)
	v_mfma_f32_16x16x32_bf16 v[84:87], v[50:53], v[100:103], v[84:87]
	ds_read_b128 v[100:103], v6 offset:17536
	ds_read_b128 v[120:123], v6 offset:17600
	s_waitcnt lgkmcnt(1)
	v_mfma_f32_16x16x32_bf16 v[88:91], v[50:53], v[100:103], v[88:91]
	ds_read_b128 v[100:103], v6 offset:21888
	ds_read_b128 v[124:127], v6 offset:21952
	v_mfma_f32_16x16x32_bf16 v[58:61], v[54:57], v[104:107], v[58:61]
	v_mfma_f32_16x16x32_bf16 v[62:65], v[54:57], v[108:111], v[62:65]
	s_waitcnt lgkmcnt(1)
	v_mfma_f32_16x16x32_bf16 v[92:95], v[50:53], v[100:103], v[92:95]
	ds_read_b128 v[100:103], v6 offset:26240
	ds_read_b128 v[104:107], v6 offset:26304
	ds_read_b128 v[108:111], v6 offset:30464
	s_nop 2
	ds_write2_b32 v38, v58, v62 offset1:16
	ds_write2_b32 v38, v59, v63 offset0:133 offset1:149
	ds_write2_b32 v39, v60, v64 offset0:10 offset1:26
	v_mfma_f32_16x16x32_bf16 v[66:69], v[54:57], v[112:115], v[66:69]
	v_mfma_f32_16x16x32_bf16 v[84:87], v[54:57], v[116:119], v[84:87]
	ds_write2_b32 v39, v61, v65 offset0:143 offset1:159
	s_nop 6
	ds_write2_b32 v38, v66, v84 offset0:33 offset1:49
	ds_read_b128 v[58:61], v6 offset:30528
	s_waitcnt lgkmcnt(6)
	v_mfma_f32_16x16x32_bf16 v[42:45], v[42:45], v[108:111], 0
	ds_write2_b32 v38, v67, v85 offset0:166 offset1:182
	ds_write2_b32 v39, v68, v86 offset0:43 offset1:59
	ds_read_b128 v[62:65], v6 offset:30592
	v_mfma_f32_16x16x32_bf16 v[88:91], v[54:57], v[120:123], v[88:91]
	v_mfma_f32_16x16x32_bf16 v[92:95], v[54:57], v[124:127], v[92:95]
	ds_write2_b32 v39, v69, v87 offset0:176 offset1:192
	s_nop 6
	ds_write2_b32 v38, v88, v92 offset0:66 offset1:82
	s_waitcnt lgkmcnt(5)
	v_mfma_f32_16x16x32_bf16 v[42:45], v[46:49], v[58:61], v[42:45]
	ds_read_b128 v[46:49], v6 offset:30656
	ds_write2_b32 v38, v89, v93 offset0:199 offset1:215
	ds_write2_b32 v39, v90, v94 offset0:76 offset1:92
	ds_write2_b32 v39, v91, v95 offset0:209 offset1:225
	v_mfma_f32_16x16x32_bf16 v[96:99], v[50:53], v[100:103], v[96:99]
	s_waitcnt lgkmcnt(6)
	v_mfma_f32_16x16x32_bf16 v[42:45], v[50:53], v[62:65], v[42:45]
	v_mfma_f32_16x16x32_bf16 v[96:99], v[54:57], v[104:107], v[96:99]
	s_waitcnt lgkmcnt(3)
	v_mfma_f32_16x16x32_bf16 v[42:45], v[54:57], v[46:49], v[42:45]
	s_nop 7
	ds_write2_b32 v38, v96, v42 offset0:99 offset1:115
	ds_write2_b32 v38, v97, v43 offset0:232 offset1:248
	ds_write2_b32 v39, v98, v44 offset0:109 offset1:125
	ds_write2_b32 v40, v99, v45 offset0:114 offset1:130
	s_waitcnt lgkmcnt(0)
	s_barrier
	ds_read2_b32 v[42:43], v22 offset1:1
	ds_read2_b32 v[44:45], v23 offset1:1
	ds_read2_b32 v[46:47], v24 offset1:1
	ds_read2_b32 v[48:49], v25 offset1:1
	s_waitcnt lgkmcnt(3)
	v_not_b32_e32 v0, v42
	v_or_b32_e32 v50, 0x80000000, v42
	v_cmp_gt_i32_e64 s[0:1], 0, v42
	s_waitcnt lgkmcnt(2)
	v_not_b32_e32 v42, v44
	v_cndmask_b32_e64 v0, v50, v0, s[0:1]
	v_or_b32_e32 v50, 0x80000000, v44
	v_cmp_gt_i32_e64 s[0:1], 0, v44
	v_or_b32_e32 v44, 0x80000000, v43
	v_and_b32_e32 v0, 0xffffff80, v0
	v_cndmask_b32_e64 v42, v50, v42, s[0:1]
	v_and_b32_e32 v42, 0xffffff80, v42
	v_sub_u32_e32 v42, v42, v78
	v_add_u32_e32 v50, 0x6f, v42
	v_not_b32_e32 v42, v43
	v_cmp_gt_i32_e64 s[0:1], 0, v43
	v_or_b32_e32 v43, 0x80000000, v45
	v_sub_u32_e32 v0, v0, v78
	v_cndmask_b32_e64 v42, v44, v42, s[0:1]
	v_and_b32_e32 v42, 0xffffff80, v42
	v_sub_u32_e32 v42, v42, v7
	v_add_u32_e32 v51, 0x7f, v42
	v_not_b32_e32 v42, v45
	v_cmp_gt_i32_e64 s[0:1], 0, v45
	v_add_u32_e32 v0, 0x7f, v0
	s_nop 0
	v_cndmask_b32_e64 v42, v43, v42, s[0:1]
	v_and_b32_e32 v42, 0xffffff80, v42
	v_sub_u32_e32 v42, v42, v7
	v_add_u32_e32 v52, 0x6f, v42
	s_waitcnt lgkmcnt(1)
	v_not_b32_e32 v42, v46
	v_or_b32_e32 v43, 0x80000000, v46
	v_cmp_gt_i32_e64 s[0:1], 0, v46
	v_max_u32_e32 v89, v50, v52
	v_min_u32_e32 v50, v50, v52
	v_cndmask_b32_e64 v42, v43, v42, s[0:1]
	v_and_b32_e32 v42, 0xffffff80, v42
	v_sub_u32_e32 v42, v42, v8
	v_add_u32_e32 v53, 0x7f, v42
	s_waitcnt lgkmcnt(0)
	v_not_b32_e32 v42, v48
	v_or_b32_e32 v43, 0x80000000, v48
	v_cmp_gt_i32_e64 s[0:1], 0, v48
	s_nop 1
	v_cndmask_b32_e64 v42, v43, v42, s[0:1]
	v_and_b32_e32 v42, 0xffffff80, v42
	v_sub_u32_e32 v42, v42, v8
	v_add_u32_e32 v54, 0x6f, v42
	v_not_b32_e32 v42, v47
	v_or_b32_e32 v43, 0x80000000, v47
	v_cmp_gt_i32_e64 s[0:1], 0, v47
	s_nop 1
	v_cndmask_b32_e64 v42, v43, v42, s[0:1]
	v_and_b32_e32 v42, 0xffffff80, v42
	v_sub_u32_e32 v42, v42, v9
	v_add_u32_e32 v55, 0x7f, v42
	v_not_b32_e32 v42, v49
	v_or_b32_e32 v43, 0x80000000, v49
	v_cmp_gt_i32_e64 s[0:1], 0, v49
	s_nop 1
	v_cndmask_b32_e64 v42, v43, v42, s[0:1]
	v_and_b32_e32 v42, 0xffffff80, v42
	v_sub_u32_e32 v44, v42, v9
	ds_read2_b32 v[42:43], v26 offset1:1
	v_add_u32_e32 v56, 0x6f, v44
	ds_read2_b32 v[44:45], v27 offset1:1
	ds_read2_b32 v[46:47], v28 offset1:1
	ds_read2_b32 v[48:49], v29 offset1:1
	v_max_u32_e32 v52, v56, v54
	v_min_u32_e32 v54, v56, v54
	s_waitcnt lgkmcnt(3)
	v_not_b32_e32 v57, v42
	v_or_b32_e32 v58, 0x80000000, v42
	v_cmp_gt_i32_e64 s[0:1], 0, v42
	s_nop 1
	v_cndmask_b32_e64 v42, v58, v57, s[0:1]
	v_and_b32_e32 v42, 0xffffff80, v42
	v_sub_u32_e32 v42, v42, v10
	v_add_u32_e32 v57, 0x7f, v42
	s_waitcnt lgkmcnt(2)
	v_not_b32_e32 v42, v44
	v_or_b32_e32 v58, 0x80000000, v44
	v_cmp_gt_i32_e64 s[0:1], 0, v44
	v_or_b32_e32 v44, 0x80000000, v43
	s_nop 0
	v_cndmask_b32_e64 v42, v58, v42, s[0:1]
	v_and_b32_e32 v42, 0xffffff80, v42
	v_sub_u32_e32 v42, v42, v10
	v_add_u32_e32 v58, 0x6f, v42
	v_not_b32_e32 v42, v43
	v_cmp_gt_i32_e64 s[0:1], 0, v43
	v_or_b32_e32 v43, 0x80000000, v45
	s_nop 0
	v_cndmask_b32_e64 v42, v44, v42, s[0:1]
	v_and_b32_e32 v42, 0xffffff80, v42
	v_sub_u32_e32 v42, v42, v11
	v_add_u32_e32 v59, 0x7f, v42
	v_not_b32_e32 v42, v45
	v_cmp_gt_i32_e64 s[0:1], 0, v45
	s_nop 1
	v_cndmask_b32_e64 v42, v43, v42, s[0:1]
	v_and_b32_e32 v42, 0xffffff80, v42
	v_sub_u32_e32 v42, v42, v11
	v_add_u32_e32 v60, 0x6f, v42
	s_waitcnt lgkmcnt(1)
	v_not_b32_e32 v42, v46
	v_or_b32_e32 v43, 0x80000000, v46
	v_cmp_gt_i32_e64 s[0:1], 0, v46
	v_max_u32_e32 v56, v58, v60
	v_min_u32_e32 v58, v58, v60
	v_cndmask_b32_e64 v42, v43, v42, s[0:1]
	v_and_b32_e32 v42, 0xffffff80, v42
	v_sub_u32_e32 v42, v42, v12
	v_add_u32_e32 v61, 0x7f, v42
	s_waitcnt lgkmcnt(0)
	v_not_b32_e32 v42, v48
	v_or_b32_e32 v43, 0x80000000, v48
	v_cmp_gt_i32_e64 s[0:1], 0, v48
	s_nop 1
	v_cndmask_b32_e64 v42, v43, v42, s[0:1]
	v_and_b32_e32 v42, 0xffffff80, v42
	v_sub_u32_e32 v42, v42, v12
	v_add_u32_e32 v62, 0x6f, v42
	v_not_b32_e32 v42, v47
	v_or_b32_e32 v43, 0x80000000, v47
	v_cmp_gt_i32_e64 s[0:1], 0, v47
	s_nop 1
	v_cndmask_b32_e64 v42, v43, v42, s[0:1]
	v_and_b32_e32 v42, 0xffffff80, v42
	v_sub_u32_e32 v42, v42, v13
	v_add_u32_e32 v63, 0x7f, v42
	v_not_b32_e32 v42, v49
	v_or_b32_e32 v43, 0x80000000, v49
	v_cmp_gt_i32_e64 s[0:1], 0, v49
	s_nop 1
	v_cndmask_b32_e64 v42, v43, v42, s[0:1]
	v_and_b32_e32 v42, 0xffffff80, v42
	v_sub_u32_e32 v44, v42, v13
	ds_read2_b32 v[42:43], v30 offset1:1
	v_add_u32_e32 v64, 0x6f, v44
	ds_read2_b32 v[44:45], v31 offset1:1
	ds_read2_b32 v[46:47], v32 offset1:1
	ds_read2_b32 v[48:49], v33 offset1:1
	v_max_u32_e32 v60, v64, v62
	v_min_u32_e32 v62, v64, v62
	s_waitcnt lgkmcnt(3)
	v_not_b32_e32 v65, v42
	v_or_b32_e32 v66, 0x80000000, v42
	v_cmp_gt_i32_e64 s[0:1], 0, v42
	s_nop 1
	v_cndmask_b32_e64 v42, v66, v65, s[0:1]
	v_and_b32_e32 v42, 0xffffff80, v42
	v_sub_u32_e32 v42, v42, v14
	v_add_u32_e32 v65, 0x7f, v42
	s_waitcnt lgkmcnt(2)
	v_not_b32_e32 v42, v44
	v_or_b32_e32 v66, 0x80000000, v44
	v_cmp_gt_i32_e64 s[0:1], 0, v44
	v_or_b32_e32 v44, 0x80000000, v43
	s_nop 0
	v_cndmask_b32_e64 v42, v66, v42, s[0:1]
	v_and_b32_e32 v42, 0xffffff80, v42
	v_sub_u32_e32 v42, v42, v14
	v_add_u32_e32 v66, 0x6f, v42
	v_not_b32_e32 v42, v43
	v_cmp_gt_i32_e64 s[0:1], 0, v43
	v_or_b32_e32 v43, 0x80000000, v45
	s_nop 0
	v_cndmask_b32_e64 v42, v44, v42, s[0:1]
	v_and_b32_e32 v42, 0xffffff80, v42
	v_sub_u32_e32 v42, v42, v15
	v_add_u32_e32 v67, 0x7f, v42
	v_not_b32_e32 v42, v45
	v_cmp_gt_i32_e64 s[0:1], 0, v45
	s_nop 1
	v_cndmask_b32_e64 v42, v43, v42, s[0:1]
	v_and_b32_e32 v42, 0xffffff80, v42
	v_sub_u32_e32 v42, v42, v15
	v_add_u32_e32 v68, 0x6f, v42
	s_waitcnt lgkmcnt(1)
	v_not_b32_e32 v42, v46
	v_or_b32_e32 v43, 0x80000000, v46
	v_cmp_gt_i32_e64 s[0:1], 0, v46
	v_max_u32_e32 v64, v66, v68
	v_min_u32_e32 v66, v66, v68
	v_cndmask_b32_e64 v42, v43, v42, s[0:1]
	v_and_b32_e32 v42, 0xffffff80, v42
	v_sub_u32_e32 v42, v42, v16
	v_add_u32_e32 v69, 0x7f, v42
	s_waitcnt lgkmcnt(0)
	v_not_b32_e32 v42, v48
	v_or_b32_e32 v43, 0x80000000, v48
	v_cmp_gt_i32_e64 s[0:1], 0, v48
	s_nop 1
	v_cndmask_b32_e64 v42, v43, v42, s[0:1]
	v_and_b32_e32 v42, 0xffffff80, v42
	v_sub_u32_e32 v42, v42, v16
	v_add_u32_e32 v70, 0x6f, v42
	v_not_b32_e32 v42, v47
	v_or_b32_e32 v43, 0x80000000, v47
	v_cmp_gt_i32_e64 s[0:1], 0, v47
	s_nop 1
	v_cndmask_b32_e64 v42, v43, v42, s[0:1]
	v_and_b32_e32 v42, 0xffffff80, v42
	v_sub_u32_e32 v42, v42, v17
	v_add_u32_e32 v71, 0x7f, v42
	v_not_b32_e32 v42, v49
	v_or_b32_e32 v43, 0x80000000, v49
	v_cmp_gt_i32_e64 s[0:1], 0, v49
	s_nop 1
	v_cndmask_b32_e64 v42, v43, v42, s[0:1]
	v_and_b32_e32 v42, 0xffffff80, v42
	v_sub_u32_e32 v44, v42, v17
	ds_read2_b32 v[42:43], v34 offset1:1
	v_add_u32_e32 v73, 0x6f, v44
	ds_read2_b32 v[44:45], v35 offset1:1
	ds_read2_b32 v[46:47], v36 offset1:1
	ds_read2_b32 v[48:49], v37 offset1:1
	v_max_u32_e32 v68, v73, v70
	v_min_u32_e32 v70, v73, v70
	s_waitcnt lgkmcnt(3)
	v_not_b32_e32 v77, v42
	v_or_b32_e32 v80, 0x80000000, v42
	v_cmp_gt_i32_e64 s[0:1], 0, v42
	s_nop 1
	v_cndmask_b32_e64 v42, v80, v77, s[0:1]
	s_waitcnt lgkmcnt(2)
	v_not_b32_e32 v77, v44
	v_or_b32_e32 v80, 0x80000000, v44
	v_cmp_gt_i32_e64 s[0:1], 0, v44
	v_and_b32_e32 v42, 0xffffff80, v42
	v_sub_u32_e32 v42, v42, v18
	v_cndmask_b32_e64 v44, v80, v77, s[0:1]
	v_not_b32_e32 v77, v43
	v_or_b32_e32 v80, 0x80000000, v43
	v_cmp_gt_i32_e64 s[0:1], 0, v43
	v_and_b32_e32 v44, 0xffffff80, v44
	v_sub_u32_e32 v44, v44, v18
	v_cndmask_b32_e64 v43, v80, v77, s[0:1]
	v_not_b32_e32 v77, v45
	v_or_b32_e32 v80, 0x80000000, v45
	v_cmp_gt_i32_e64 s[0:1], 0, v45
	v_and_b32_e32 v43, 0xffffff80, v43
	v_sub_u32_e32 v43, v43, v19
	v_cndmask_b32_e64 v45, v80, v77, s[0:1]
	s_waitcnt lgkmcnt(1)
	v_not_b32_e32 v77, v46
	v_or_b32_e32 v80, 0x80000000, v46
	v_cmp_gt_i32_e64 s[0:1], 0, v46
	v_and_b32_e32 v45, 0xffffff80, v45
	v_sub_u32_e32 v45, v45, v19
	v_cndmask_b32_e64 v46, v80, v77, s[0:1]
	s_waitcnt lgkmcnt(0)
	v_not_b32_e32 v77, v48
	v_or_b32_e32 v80, 0x80000000, v48
	v_cmp_gt_i32_e64 s[0:1], 0, v48
	v_and_b32_e32 v46, 0xffffff80, v46
	v_sub_u32_e32 v46, v46, v20
	v_cndmask_b32_e64 v48, v80, v77, s[0:1]
	v_not_b32_e32 v77, v47
	v_or_b32_e32 v80, 0x80000000, v47
	v_cmp_gt_i32_e64 s[0:1], 0, v47
	v_and_b32_e32 v48, 0xffffff80, v48
	v_sub_u32_e32 v48, v48, v20
	v_cndmask_b32_e64 v47, v80, v77, s[0:1]
	v_not_b32_e32 v77, v49
	v_or_b32_e32 v80, 0x80000000, v49
	v_cmp_gt_i32_e64 s[0:1], 0, v49
	v_and_b32_e32 v47, 0xffffff80, v47
	v_sub_u32_e32 v47, v47, v21
	v_cndmask_b32_e64 v49, v80, v77, s[0:1]
	v_and_b32_e32 v49, 0xffffff80, v49
	v_sub_u32_e32 v49, v49, v21
	v_add_u32_e32 v42, 0x7f, v42
	v_add_u32_e32 v44, 0x6f, v44
	v_add_u32_e32 v43, 0x7f, v43
	v_add_u32_e32 v45, 0x6f, v45
	v_add_u32_e32 v46, 0x7f, v46
	v_add_u32_e32 v48, 0x6f, v48
	v_add_u32_e32 v47, 0x7f, v47
	v_add_u32_e32 v49, 0x6f, v49
	v_max_u32_e32 v77, v0, v51
	v_min_u32_e32 v0, v0, v51
	v_max_u32_e32 v51, v55, v53
	v_min_u32_e32 v53, v55, v53
	v_max_u32_e32 v55, v57, v59
	v_min_u32_e32 v57, v57, v59
	v_max_u32_e32 v59, v63, v61
	v_min_u32_e32 v61, v63, v61
	v_max_u32_e32 v63, v65, v67
	v_min_u32_e32 v65, v65, v67
	v_max_u32_e32 v67, v71, v69
	v_min_u32_e32 v69, v71, v69
	v_max_u32_e32 v71, v42, v43
	v_min_u32_e32 v42, v42, v43
	v_max_u32_e32 v43, v47, v46
	v_min_u32_e32 v46, v47, v46
	v_max_u32_e32 v73, v44, v45
	v_min_u32_e32 v44, v44, v45
	v_max_u32_e32 v45, v49, v48
	v_min_u32_e32 v48, v49, v48
	v_max_u32_e32 v47, v77, v53
	v_min_u32_e32 v53, v77, v53
	v_max_u32_e32 v77, v0, v51
	v_min_u32_e32 v0, v0, v51
	v_max_u32_e32 v51, v61, v55
	v_min_u32_e32 v55, v61, v55
	v_max_u32_e32 v61, v59, v57
	v_min_u32_e32 v57, v59, v57
	v_max_u32_e32 v59, v63, v69
	v_min_u32_e32 v63, v63, v69
	v_max_u32_e32 v69, v65, v67
	v_min_u32_e32 v65, v65, v67
	v_max_u32_e32 v67, v46, v71
	v_min_u32_e32 v46, v46, v71
	v_max_u32_e32 v71, v43, v42
	v_min_u32_e32 v42, v43, v42
	v_max_u32_e32 v49, v89, v54
	v_min_u32_e32 v54, v89, v54
	v_max_u32_e32 v89, v50, v52
	v_min_u32_e32 v50, v50, v52
	v_max_u32_e32 v52, v62, v56
	v_min_u32_e32 v56, v62, v56
	v_max_u32_e32 v62, v60, v58
	v_min_u32_e32 v58, v60, v58
	v_max_u32_e32 v60, v64, v70
	v_min_u32_e32 v64, v64, v70
	v_max_u32_e32 v70, v66, v68
	v_min_u32_e32 v66, v66, v68
	v_max_u32_e32 v68, v48, v73
	v_min_u32_e32 v48, v48, v73
	v_max_u32_e32 v73, v45, v44
	v_min_u32_e32 v44, v45, v44
	v_max_u32_e32 v43, v47, v77
	v_min_u32_e32 v47, v47, v77
	v_max_u32_e32 v77, v53, v0
	v_min_u32_e32 v0, v53, v0
	v_max_u32_e32 v53, v57, v55
	v_min_u32_e32 v55, v57, v55
	v_max_u32_e32 v57, v61, v51
	v_min_u32_e32 v51, v61, v51
	v_max_u32_e32 v61, v59, v69
	v_min_u32_e32 v59, v59, v69
	v_max_u32_e32 v69, v63, v65
	v_min_u32_e32 v63, v63, v65
	v_max_u32_e32 v65, v42, v46
	v_min_u32_e32 v42, v42, v46
	v_max_u32_e32 v46, v71, v67
	v_min_u32_e32 v67, v71, v67
	v_max_u32_e32 v45, v49, v89
	v_min_u32_e32 v49, v49, v89
	v_max_u32_e32 v89, v54, v50
	v_min_u32_e32 v50, v54, v50
	v_max_u32_e32 v54, v58, v56
	v_min_u32_e32 v56, v58, v56
	v_max_u32_e32 v58, v62, v52
	v_min_u32_e32 v52, v62, v52
	v_max_u32_e32 v62, v60, v70
	v_min_u32_e32 v60, v60, v70
	v_max_u32_e32 v70, v64, v66
	v_min_u32_e32 v64, v64, v66
	v_max_u32_e32 v66, v44, v48
	v_min_u32_e32 v44, v44, v48
	v_max_u32_e32 v48, v73, v68
	v_min_u32_e32 v68, v73, v68
	v_max_u32_e32 v71, v43, v55
	v_min_u32_e32 v43, v43, v55
	v_max_u32_e32 v55, v47, v53
	v_min_u32_e32 v47, v47, v53
	v_max_u32_e32 v53, v77, v51
	v_min_u32_e32 v51, v77, v51
	v_max_u32_e32 v77, v0, v57
	v_min_u32_e32 v0, v0, v57
	v_max_u32_e32 v57, v42, v61
	v_min_u32_e32 v42, v42, v61
	v_max_u32_e32 v61, v65, v59
	v_min_u32_e32 v59, v65, v59
	v_max_u32_e32 v65, v67, v69
	v_min_u32_e32 v67, v67, v69
	v_max_u32_e32 v69, v46, v63
	v_min_u32_e32 v46, v46, v63
	v_max_u32_e32 v73, v45, v56
	v_min_u32_e32 v45, v45, v56
	v_max_u32_e32 v56, v49, v54
	v_min_u32_e32 v49, v49, v54
	v_max_u32_e32 v54, v89, v52
	v_min_u32_e32 v52, v89, v52
	v_max_u32_e32 v89, v50, v58
	v_min_u32_e32 v50, v50, v58
	v_max_u32_e32 v58, v44, v62
	v_min_u32_e32 v44, v44, v62
	v_max_u32_e32 v62, v66, v60
	v_min_u32_e32 v60, v66, v60
	v_max_u32_e32 v66, v68, v70
	v_min_u32_e32 v68, v68, v70
	v_max_u32_e32 v70, v48, v64
	v_min_u32_e32 v48, v48, v64
	v_max_u32_e32 v63, v71, v53
	v_min_u32_e32 v53, v71, v53
	v_max_u32_e32 v71, v55, v77
	v_min_u32_e32 v55, v55, v77
	v_max_u32_e32 v77, v43, v51
	v_min_u32_e32 v43, v43, v51
	v_max_u32_e32 v51, v47, v0
	v_min_u32_e32 v0, v47, v0
	v_max_u32_e32 v47, v67, v42
	v_min_u32_e32 v42, v67, v42
	v_max_u32_e32 v67, v46, v59
	v_min_u32_e32 v46, v46, v59
	v_max_u32_e32 v59, v65, v57
	v_min_u32_e32 v57, v65, v57
	v_max_u32_e32 v65, v69, v61
	v_min_u32_e32 v61, v69, v61
	v_max_u32_e32 v64, v73, v54
	v_min_u32_e32 v54, v73, v54
	v_max_u32_e32 v73, v56, v89
	v_min_u32_e32 v56, v56, v89
	v_max_u32_e32 v89, v45, v52
	v_min_u32_e32 v45, v45, v52
	v_max_u32_e32 v52, v49, v50
	v_min_u32_e32 v49, v49, v50
	v_max_u32_e32 v50, v68, v44
	v_min_u32_e32 v44, v68, v44
	v_max_u32_e32 v68, v48, v60
	v_min_u32_e32 v48, v48, v60
	v_max_u32_e32 v60, v66, v58
	v_min_u32_e32 v58, v66, v58
	v_max_u32_e32 v66, v70, v62
	v_min_u32_e32 v62, v70, v62
	v_max_u32_e32 v69, v63, v71
	v_min_u32_e32 v63, v63, v71
	v_max_u32_e32 v71, v53, v55
	v_min_u32_e32 v53, v53, v55
	v_max_u32_e32 v55, v77, v51
	v_min_u32_e32 v51, v77, v51
	v_max_u32_e32 v77, v43, v0
	v_min_u32_e32 v0, v43, v0
	v_max_u32_e32 v43, v46, v42
	v_min_u32_e32 v42, v46, v42
	v_max_u32_e32 v46, v67, v47
	v_min_u32_e32 v47, v67, v47
	v_max_u32_e32 v67, v61, v57
	v_min_u32_e32 v57, v61, v57
	v_max_u32_e32 v61, v65, v59
	v_min_u32_e32 v59, v65, v59
	v_max_u32_e32 v70, v64, v73
	v_min_u32_e32 v64, v64, v73
	v_max_u32_e32 v73, v54, v56
	v_min_u32_e32 v54, v54, v56
	v_max_u32_e32 v56, v89, v52
	v_min_u32_e32 v52, v89, v52
	v_max_u32_e32 v89, v45, v49
	v_min_u32_e32 v45, v45, v49
	v_max_u32_e32 v49, v48, v44
	v_min_u32_e32 v44, v48, v44
	v_max_u32_e32 v48, v68, v50
	v_min_u32_e32 v50, v68, v50
	v_max_u32_e32 v68, v62, v58
	v_min_u32_e32 v58, v62, v58
	v_max_u32_e32 v62, v66, v60
	v_min_u32_e32 v60, v66, v60
	v_max_u32_e32 v65, v69, v42
	v_min_u32_e32 v42, v69, v42
	v_max_u32_e32 v69, v63, v43
	v_min_u32_e32 v43, v63, v43
	v_max_u32_e32 v63, v71, v47
	v_min_u32_e32 v47, v71, v47
	v_max_u32_e32 v71, v53, v46
	v_min_u32_e32 v46, v53, v46
	v_max_u32_e32 v53, v55, v57
	v_min_u32_e32 v55, v55, v57
	v_max_u32_e32 v57, v51, v67
	v_min_u32_e32 v51, v51, v67
	v_max_u32_e32 v67, v77, v59
	v_min_u32_e32 v59, v77, v59
	v_max_u32_e32 v77, v0, v61
	v_min_u32_e32 v0, v0, v61
	v_max_u32_e32 v66, v70, v44
	v_min_u32_e32 v44, v70, v44
	v_max_u32_e32 v70, v64, v49
	v_min_u32_e32 v49, v64, v49
	v_max_u32_e32 v64, v73, v50
	v_min_u32_e32 v50, v73, v50
	v_max_u32_e32 v73, v54, v48
	v_min_u32_e32 v48, v54, v48
	v_max_u32_e32 v54, v56, v58
	v_min_u32_e32 v56, v56, v58
	v_max_u32_e32 v58, v52, v68
	v_min_u32_e32 v52, v52, v68
	v_max_u32_e32 v68, v89, v60
	v_min_u32_e32 v60, v89, v60
	v_max_u32_e32 v89, v45, v62
	v_min_u32_e32 v45, v45, v62
	v_max_u32_e32 v61, v65, v53
	v_min_u32_e32 v53, v65, v53
	v_max_u32_e32 v65, v69, v57
	v_min_u32_e32 v57, v69, v57
	v_max_u32_e32 v69, v63, v67
	v_min_u32_e32 v63, v63, v67
	v_max_u32_e32 v67, v71, v77
	v_min_u32_e32 v71, v71, v77
	v_max_u32_e32 v77, v42, v55
	v_min_u32_e32 v42, v42, v55
	v_max_u32_e32 v55, v43, v51
	v_min_u32_e32 v43, v43, v51
	v_max_u32_e32 v51, v47, v59
	v_min_u32_e32 v47, v47, v59
	v_max_u32_e32 v59, v46, v0
	v_min_u32_e32 v0, v46, v0
	v_max_u32_e32 v62, v66, v54
	v_min_u32_e32 v54, v66, v54
	v_max_u32_e32 v66, v70, v58
	v_min_u32_e32 v58, v70, v58
	v_max_u32_e32 v70, v64, v68
	v_min_u32_e32 v64, v64, v68
	v_max_u32_e32 v68, v73, v89
	v_min_u32_e32 v73, v73, v89
	v_max_u32_e32 v89, v44, v56
	v_min_u32_e32 v44, v44, v56
	v_max_u32_e32 v56, v49, v52
	v_min_u32_e32 v49, v49, v52
	v_max_u32_e32 v52, v50, v60
	v_min_u32_e32 v50, v50, v60
	v_max_u32_e32 v60, v48, v45
	v_min_u32_e32 v45, v48, v45
	v_max_u32_e32 v46, v61, v69
	v_min_u32_e32 v61, v61, v69
	v_max_u32_e32 v69, v65, v67
	v_min_u32_e32 v65, v65, v67
	v_max_u32_e32 v67, v53, v63
	v_min_u32_e32 v53, v53, v63
	v_max_u32_e32 v63, v57, v71
	v_min_u32_e32 v57, v57, v71
	v_max_u32_e32 v71, v77, v51
	v_min_u32_e32 v51, v77, v51
	v_max_u32_e32 v77, v55, v59
	v_min_u32_e32 v55, v55, v59
	v_max_u32_e32 v59, v42, v47
	v_min_u32_e32 v42, v42, v47
	v_max_u32_e32 v47, v43, v0
	v_min_u32_e32 v0, v43, v0
	v_max_u32_e32 v48, v62, v70
	v_min_u32_e32 v62, v62, v70
	v_max_u32_e32 v70, v66, v68
	v_min_u32_e32 v66, v66, v68
	v_max_u32_e32 v68, v54, v64
	v_min_u32_e32 v54, v54, v64
	v_max_u32_e32 v64, v58, v73
	v_min_u32_e32 v58, v58, v73
	v_max_u32_e32 v73, v89, v52
	v_min_u32_e32 v52, v89, v52
	v_max_u32_e32 v89, v56, v60
	v_min_u32_e32 v56, v56, v60
	v_max_u32_e32 v60, v44, v50
	v_min_u32_e32 v44, v44, v50
	v_max_u32_e32 v50, v49, v45
	v_min_u32_e32 v45, v49, v45
	v_min_u32_e32 v43, v46, v69
	v_min_u32_e32 v80, v61, v65
	v_min_u32_e32 v82, v67, v63
	v_min_u32_e32 v84, v53, v57
	v_min_u32_e32 v85, v71, v77
	v_min_u32_e32 v86, v51, v55
	v_min_u32_e32 v87, v59, v47
	v_min_u32_e32 v88, v42, v0
	v_min_u32_e32 v49, v48, v70
	v_min_u32_e32 v90, v62, v66
	v_min_u32_e32 v91, v68, v64
	v_min_u32_e32 v92, v54, v58
	v_min_u32_e32 v93, v73, v89
	v_min_u32_e32 v94, v52, v56
	v_min_u32_e32 v95, v60, v50
	v_min_u32_e32 v96, v44, v45
	v_max3_u32 v46, v46, v69, v96
	v_max3_u32 v43, v43, v44, v45
	v_max3_u32 v44, v61, v65, v95
	v_max3_u32 v45, v80, v60, v50
	v_max3_u32 v50, v67, v63, v94
	v_max3_u32 v52, v82, v52, v56
	v_max3_u32 v53, v53, v57, v93
	v_max3_u32 v56, v84, v73, v89
	v_max3_u32 v57, v71, v77, v92
	v_max3_u32 v54, v85, v54, v58
	v_max3_u32 v51, v51, v55, v91
	v_max3_u32 v55, v86, v68, v64
	v_max3_u32 v47, v59, v47, v90
	v_max3_u32 v58, v87, v62, v66
	v_max3_u32 v0, v42, v0, v49
	v_max3_u32 v42, v88, v48, v70
	v_max_u32_e32 v48, v46, v57
	v_min_u32_e32 v46, v46, v57
	v_max_u32_e32 v49, v43, v54
	v_min_u32_e32 v43, v43, v54
	v_max_u32_e32 v54, v44, v51
	v_min_u32_e32 v44, v44, v51
	v_max_u32_e32 v51, v45, v55
	v_min_u32_e32 v45, v45, v55
	v_max_u32_e32 v55, v50, v47
	v_min_u32_e32 v47, v50, v47
	v_max_u32_e32 v50, v52, v58
	v_min_u32_e32 v52, v52, v58
	v_max_u32_e32 v57, v53, v0
	v_min_u32_e32 v0, v53, v0
	v_max_u32_e32 v53, v56, v42
	v_min_u32_e32 v42, v56, v42
	v_max_u32_e32 v56, v48, v55
	v_min_u32_e32 v48, v48, v55
	v_max_u32_e32 v55, v49, v50
	v_min_u32_e32 v49, v49, v50
	v_max_u32_e32 v50, v54, v57
	v_min_u32_e32 v54, v54, v57
	v_max_u32_e32 v57, v51, v53
	v_min_u32_e32 v51, v51, v53
	v_max_u32_e32 v53, v46, v47
	v_min_u32_e32 v46, v46, v47
	v_max_u32_e32 v47, v43, v52
	v_min_u32_e32 v43, v43, v52
	v_max_u32_e32 v52, v44, v0
	v_min_u32_e32 v0, v44, v0
	v_max_u32_e32 v44, v45, v42
	v_min_u32_e32 v42, v45, v42
	v_max_u32_e32 v45, v56, v50
	v_min_u32_e32 v50, v56, v50
	v_max_u32_e32 v56, v55, v57
	v_min_u32_e32 v55, v55, v57
	v_max_u32_e32 v57, v48, v54
	v_min_u32_e32 v48, v48, v54
	v_max_u32_e32 v54, v49, v51
	v_min_u32_e32 v49, v49, v51
	v_max_u32_e32 v51, v53, v52
	v_min_u32_e32 v52, v53, v52
	v_max_u32_e32 v53, v47, v44
	v_min_u32_e32 v44, v47, v44
	v_max_u32_e32 v47, v46, v0
	v_min_u32_e32 v0, v46, v0
	v_max_u32_e32 v46, v43, v42
	v_min_u32_e32 v42, v43, v42
	v_max_u32_e32 v43, v45, v56
	v_min_u32_e32 v45, v45, v56
	v_max_u32_e32 v56, v50, v55
	v_min_u32_e32 v50, v50, v55
	v_max_u32_e32 v55, v57, v54
	v_min_u32_e32 v54, v57, v54
	v_max_u32_e32 v57, v48, v49
	v_min_u32_e32 v48, v48, v49
	v_max_u32_e32 v49, v51, v53
	v_min_u32_e32 v51, v51, v53
	v_max_u32_e32 v53, v52, v44
	v_min_u32_e32 v44, v52, v44
	v_max_u32_e32 v52, v47, v46
	v_min_u32_e32 v46, v47, v46
	v_max_u32_e32 v47, v0, v42
	v_min_u32_e32 v0, v0, v42
	v_max_u32_dpp v59, v46, v56 quad_perm:[1,0,3,2] row_mask:0xf bank_mask:0xf bound_ctrl:1
	v_max_u32_dpp v58, v47, v45 quad_perm:[1,0,3,2] row_mask:0xf bank_mask:0xf bound_ctrl:1
	v_max_u32_dpp v42, v0, v43 quad_perm:[1,0,3,2] row_mask:0xf bank_mask:0xf bound_ctrl:1
	v_max_u32_dpp v60, v52, v50 quad_perm:[1,0,3,2] row_mask:0xf bank_mask:0xf bound_ctrl:1
	v_max_u32_dpp v61, v44, v55 quad_perm:[1,0,3,2] row_mask:0xf bank_mask:0xf bound_ctrl:1
	v_max_u32_dpp v62, v53, v54 quad_perm:[1,0,3,2] row_mask:0xf bank_mask:0xf bound_ctrl:1
	v_max_u32_dpp v63, v51, v57 quad_perm:[1,0,3,2] row_mask:0xf bank_mask:0xf bound_ctrl:1
	v_max_u32_dpp v64, v49, v48 quad_perm:[1,0,3,2] row_mask:0xf bank_mask:0xf bound_ctrl:1
	v_max_u32_dpp v48, v48, v49 quad_perm:[1,0,3,2] row_mask:0xf bank_mask:0xf bound_ctrl:1
	v_max_u32_dpp v49, v57, v51 quad_perm:[1,0,3,2] row_mask:0xf bank_mask:0xf bound_ctrl:1
	v_max_u32_dpp v51, v54, v53 quad_perm:[1,0,3,2] row_mask:0xf bank_mask:0xf bound_ctrl:1
	v_max_u32_dpp v44, v55, v44 quad_perm:[1,0,3,2] row_mask:0xf bank_mask:0xf bound_ctrl:1
	v_max_u32_dpp v50, v50, v52 quad_perm:[1,0,3,2] row_mask:0xf bank_mask:0xf bound_ctrl:1
	v_max_u32_dpp v46, v56, v46 quad_perm:[1,0,3,2] row_mask:0xf bank_mask:0xf bound_ctrl:1
	v_max_u32_dpp v45, v45, v47 quad_perm:[1,0,3,2] row_mask:0xf bank_mask:0xf bound_ctrl:1
	v_max_u32_dpp v0, v43, v0 quad_perm:[1,0,3,2] row_mask:0xf bank_mask:0xf bound_ctrl:1
	v_max_u32_e32 v43, v42, v48
	v_min_u32_e32 v42, v42, v48
	v_max_u32_e32 v47, v58, v49
	v_min_u32_e32 v48, v58, v49
	v_max_u32_e32 v49, v59, v51
	v_min_u32_e32 v51, v59, v51
	v_max_u32_e32 v52, v60, v44
	v_min_u32_e32 v44, v60, v44
	v_max_u32_e32 v53, v61, v50
	v_min_u32_e32 v50, v61, v50
	v_max_u32_e32 v54, v62, v46
	v_min_u32_e32 v46, v62, v46
	v_max_u32_e32 v55, v63, v45
	v_min_u32_e32 v45, v63, v45
	v_max_u32_e32 v56, v64, v0
	v_min_u32_e32 v0, v64, v0
	v_max_u32_e32 v57, v43, v53
	v_min_u32_e32 v43, v43, v53
	v_max_u32_e32 v53, v47, v54
	v_min_u32_e32 v47, v47, v54
	v_max_u32_e32 v54, v49, v55
	v_min_u32_e32 v49, v49, v55
	v_max_u32_e32 v55, v52, v56
	v_min_u32_e32 v52, v52, v56
	v_max_u32_e32 v56, v42, v50
	v_min_u32_e32 v42, v42, v50
	v_max_u32_e32 v50, v48, v46
	v_min_u32_e32 v46, v48, v46
	v_max_u32_e32 v48, v51, v45
	v_min_u32_e32 v45, v51, v45
	v_max_u32_e32 v51, v44, v0
	v_min_u32_e32 v0, v44, v0
	v_max_u32_e32 v44, v57, v54
	v_min_u32_e32 v54, v57, v54
	v_max_u32_e32 v57, v53, v55
	v_min_u32_e32 v53, v53, v55
	v_max_u32_e32 v58, v43, v49
	v_min_u32_e32 v49, v43, v49
	v_max_u32_e32 v59, v47, v52
	v_min_u32_e32 v47, v47, v52
	v_max_u32_e32 v52, v56, v48
	v_min_u32_e32 v60, v56, v48
	v_max_u32_e32 v48, v50, v51
	v_min_u32_e32 v61, v50, v51
	v_max_u32_e32 v64, v42, v45
	v_min_u32_e32 v65, v42, v45
	v_max_u32_e32 v66, v46, v0
	v_min_u32_e32 v46, v46, v0
	v_max_u32_e32 v55, v44, v57
	v_min_u32_e32 v43, v44, v57
	v_max_u32_e32 v50, v54, v53
	v_min_u32_e32 v0, v54, v53
	v_max_u32_e32 v56, v58, v59
	v_min_u32_e32 v44, v58, v59
	v_max_u32_e32 v51, v49, v47
	v_min_u32_e32 v42, v49, v47
	v_max_u32_e32 v62, v52, v48
	v_min_u32_e32 v48, v52, v48
	v_max_u32_e32 v57, v60, v61
	v_min_u32_e32 v45, v60, v61
	v_max_u32_e32 v63, v64, v66
	v_min_u32_e32 v49, v64, v66
	v_max_u32_e32 v58, v65, v46
	v_min_u32_e32 v46, v65, v46
	v_mov_b32_dpp v47, v55 quad_perm:[2,3,0,1] row_mask:0xf bank_mask:0xf bound_ctrl:1
	v_mov_b32_dpp v59, v43 quad_perm:[2,3,0,1] row_mask:0xf bank_mask:0xf bound_ctrl:1
	v_mov_b32_dpp v53, v50 quad_perm:[2,3,0,1] row_mask:0xf bank_mask:0xf bound_ctrl:1
	v_mov_b32_dpp v66, v0 quad_perm:[2,3,0,1] row_mask:0xf bank_mask:0xf bound_ctrl:1
	v_mov_b32_dpp v52, v56 quad_perm:[2,3,0,1] row_mask:0xf bank_mask:0xf bound_ctrl:1
	v_mov_b32_dpp v65, v44 quad_perm:[2,3,0,1] row_mask:0xf bank_mask:0xf bound_ctrl:1
	v_mov_b32_dpp v60, v51 quad_perm:[2,3,0,1] row_mask:0xf bank_mask:0xf bound_ctrl:1
	v_mov_b32_dpp v69, v42 quad_perm:[2,3,0,1] row_mask:0xf bank_mask:0xf bound_ctrl:1
	v_mov_b32_dpp v54, v62 quad_perm:[2,3,0,1] row_mask:0xf bank_mask:0xf bound_ctrl:1
	v_mov_b32_dpp v67, v48 quad_perm:[2,3,0,1] row_mask:0xf bank_mask:0xf bound_ctrl:1
	v_mov_b32_dpp v64, v57 quad_perm:[2,3,0,1] row_mask:0xf bank_mask:0xf bound_ctrl:1
	v_mov_b32_dpp v71, v45 quad_perm:[2,3,0,1] row_mask:0xf bank_mask:0xf bound_ctrl:1
	v_mov_b32_dpp v61, v63 quad_perm:[2,3,0,1] row_mask:0xf bank_mask:0xf bound_ctrl:1
	v_mov_b32_dpp v70, v49 quad_perm:[2,3,0,1] row_mask:0xf bank_mask:0xf bound_ctrl:1
	v_mov_b32_dpp v68, v58 quad_perm:[2,3,0,1] row_mask:0xf bank_mask:0xf bound_ctrl:1
	v_mov_b32_dpp v73, v46 quad_perm:[2,3,0,1] row_mask:0xf bank_mask:0xf bound_ctrl:1
	s_and_saveexec_b64 s[0:1], vcc
	s_cbranch_execz .LBB0_948
	v_max_u32_e32 v55, v55, v73
	v_max_u32_e32 v62, v62, v69
	v_max_u32_e32 v56, v56, v71
	v_max_u32_e32 v63, v63, v66
	v_max_u32_e32 v50, v50, v70
	v_max_u32_e32 v57, v57, v65
	v_max_u32_e32 v51, v51, v67
	v_max_u32_e32 v58, v58, v59
	v_max_u32_e32 v43, v43, v68
	v_max_u32_e32 v48, v48, v60
	v_max_u32_e32 v44, v44, v64
	v_max_u32_e32 v49, v49, v53
	v_max_u32_e32 v0, v0, v61
	v_max_u32_e32 v45, v45, v52
	v_max_u32_e32 v42, v42, v54
	v_max_u32_e32 v46, v46, v47
	v_min_u32_e32 v69, v55, v62
	v_min_u32_e32 v66, v56, v63
	v_min_u32_e32 v65, v50, v57
	v_min_u32_e32 v59, v51, v58
	v_min_u32_e32 v60, v43, v48
	v_min_u32_e32 v53, v44, v49
	v_min_u32_e32 v52, v0, v45
	v_min_u32_e32 v47, v42, v46
	v_min_u32_e32 v71, v69, v66
	v_min_u32_e32 v67, v65, v59
	v_min_u32_e32 v64, v60, v53
	v_min_u32_e32 v54, v52, v47
	v_min_u32_e32 v70, v71, v67
	v_min_u32_e32 v61, v64, v54
	v_max_u32_e32 v67, v71, v67
	v_max_u32_e32 v54, v64, v54
	v_min_u32_e32 v64, v67, v54
	v_max_u32_e32 v67, v67, v54
	v_max_u32_e32 v54, v69, v66
	v_max_u32_e32 v59, v65, v59
	v_max_u32_e32 v53, v60, v53
	v_max_u32_e32 v47, v52, v47
	v_min_u32_e32 v65, v54, v59
	v_min_u32_e32 v52, v53, v47
	v_min_u32_e32 v60, v65, v52
	v_max_u32_e32 v65, v65, v52
	v_max_u32_e32 v52, v54, v59
	v_max_u32_e32 v47, v53, v47
	v_min_u32_e32 v59, v52, v47
	v_max_u32_e32 v66, v52, v47
	v_max_u32_e32 v47, v55, v62
	v_max_u32_e32 v52, v56, v63
	v_max_u32_e32 v50, v50, v57
	v_max_u32_e32 v51, v51, v58
	v_max_u32_e32 v43, v43, v48
	v_max_u32_e32 v44, v44, v49
	v_max_u32_e32 v0, v0, v45
	v_max_u32_e32 v42, v42, v46
	v_min_u32_e32 v53, v47, v52
	v_min_u32_e32 v54, v50, v51
	v_min_u32_e32 v48, v43, v44
	v_min_u32_e32 v45, v0, v42
	v_min_u32_e32 v55, v53, v54
	v_min_u32_e32 v46, v48, v45
	v_min_u32_e32 v49, v55, v46
	v_max_u32_e32 v55, v55, v46
	v_max_u32_e32 v46, v53, v54
	v_max_u32_e32 v45, v48, v45
	v_min_u32_e32 v48, v46, v45
	v_max_u32_e32 v46, v46, v45
	v_max_u32_e32 v45, v47, v52
	v_max_u32_e32 v47, v50, v51
	v_max_u32_e32 v43, v43, v44
	v_max_u32_e32 v0, v0, v42
	v_min_u32_e32 v50, v45, v47
	v_min_u32_e32 v42, v43, v0
	v_min_u32_e32 v44, v50, v42
	v_max_u32_e32 v50, v50, v42
	v_max_u32_e32 v42, v45, v47
	v_max_u32_e32 v0, v43, v0
	v_min_u32_e32 v43, v42, v0
	v_max_u32_e32 v0, v42, v0
	v_or_b32_e32 v42, s18, v5
	v_lshlrev_b32_e32 v42, 7, v42
	v_lshlrev_b32_e32 v41, 4, v41
	v_add_lshl_u32 v41, v42, v41, 2
	v_xor_b32_e32 v42, -1, v43
	v_xor_b32_e32 v0, -1, v0
	v_and_b32_e32 v43, 0x7f, v42
	v_and_b32_e32 v42, 0x7f, v0
	v_lshrrev_b32_e32 v0, 3, v42
	v_and_b32_e32 v0, 12, v0
	v_lshlrev_b32_e32 v45, 2, v42
	v_add3_u32 v0, v4, v0, v45
	v_lshrrev_b32_e32 v45, 3, v43
	v_and_b32_e32 v45, 12, v45
	v_lshlrev_b32_e32 v47, 2, v43
	v_add3_u32 v51, v4, v45, v47
	v_xor_b32_e32 v44, -1, v44
	v_xor_b32_e32 v47, -1, v50
	v_and_b32_e32 v45, 0x7f, v44
	v_and_b32_e32 v44, 0x7f, v47
	v_lshrrev_b32_e32 v47, 3, v44
	v_and_b32_e32 v47, 12, v47
	v_lshlrev_b32_e32 v50, 2, v44
	v_add3_u32 v52, v4, v47, v50
	v_lshrrev_b32_e32 v47, 3, v45
	v_xor_b32_e32 v46, -1, v46
	v_and_b32_e32 v47, 12, v47
	v_lshlrev_b32_e32 v50, 2, v45
	v_and_b32_e32 v46, 0x7f, v46
	v_add3_u32 v53, v4, v47, v50
	v_xor_b32_e32 v47, -1, v48
	v_lshrrev_b32_e32 v48, 3, v46
	v_and_b32_e32 v47, 0x7f, v47
	v_and_b32_e32 v48, 12, v48
	v_lshlrev_b32_e32 v50, 2, v46
	v_add3_u32 v54, v4, v48, v50
	v_lshrrev_b32_e32 v48, 3, v47
	v_and_b32_e32 v48, 12, v48
	v_lshlrev_b32_e32 v50, 2, v47
	v_add3_u32 v56, v4, v48, v50
	v_xor_b32_e32 v48, -1, v49
	v_xor_b32_e32 v50, -1, v55
	v_and_b32_e32 v49, 0x7f, v48
	v_and_b32_e32 v48, 0x7f, v50
	v_lshrrev_b32_e32 v50, 3, v48
	v_and_b32_e32 v50, 12, v50
	v_lshlrev_b32_e32 v55, 2, v48
	v_add3_u32 v57, v4, v50, v55
	v_lshrrev_b32_e32 v50, 3, v49
	v_and_b32_e32 v50, 12, v50
	v_lshlrev_b32_e32 v55, 2, v49
	v_add3_u32 v58, v4, v50, v55
	ds_read_b32 v50, v0 offset:34816
	ds_read_b32 v51, v51 offset:34816
	ds_read_b32 v52, v52 offset:34816
	ds_read_b32 v53, v53 offset:34816
	ds_read_b32 v54, v54 offset:34816
	ds_read_b32 v55, v56 offset:34816
	ds_read_b32 v56, v57 offset:34816
	ds_read_b32 v57, v58 offset:34816
	s_waitcnt lgkmcnt(4)
	global_store_dwordx4 v41, v[50:53], s[4:5]
	global_store_dwordx4 v41, v[42:45], s[10:11]
	v_xor_b32_e32 v0, -1, v59
	v_xor_b32_e32 v50, -1, v65
	v_xor_b32_e32 v42, -1, v66
	v_and_b32_e32 v42, 0x7f, v42
	v_and_b32_e32 v43, 0x7f, v0
	v_lshrrev_b32_e32 v0, 3, v42
	v_and_b32_e32 v0, 12, v0
	v_lshlrev_b32_e32 v44, 2, v42
	v_add3_u32 v0, v4, v0, v44
	v_lshrrev_b32_e32 v44, 3, v43
	v_and_b32_e32 v44, 12, v44
	v_lshlrev_b32_e32 v45, 2, v43
	v_add3_u32 v59, v4, v44, v45
	v_xor_b32_e32 v44, -1, v60
	v_and_b32_e32 v45, 0x7f, v44
	v_and_b32_e32 v44, 0x7f, v50
	v_lshrrev_b32_e32 v50, 3, v44
	v_and_b32_e32 v50, 12, v50
	v_lshlrev_b32_e32 v51, 2, v44
	v_add3_u32 v60, v4, v50, v51
	v_lshrrev_b32_e32 v50, 3, v45
	v_and_b32_e32 v50, 12, v50
	v_lshlrev_b32_e32 v51, 2, v45
	v_add3_u32 v62, v4, v50, v51
	v_xor_b32_e32 v50, -1, v64
	v_xor_b32_e32 v52, -1, v67
	v_and_b32_e32 v51, 0x7f, v50
	v_and_b32_e32 v50, 0x7f, v52
	v_lshrrev_b32_e32 v52, 3, v50
	v_and_b32_e32 v52, 12, v52
	v_lshlrev_b32_e32 v53, 2, v50
	v_add3_u32 v63, v4, v52, v53
	v_lshrrev_b32_e32 v52, 3, v51
	v_min_u32_e32 v68, v70, v61
	v_max_u32_e32 v61, v70, v61
	v_and_b32_e32 v52, 12, v52
	v_lshlrev_b32_e32 v53, 2, v51
	v_add3_u32 v64, v4, v52, v53
	v_xor_b32_e32 v52, -1, v68
	v_xor_b32_e32 v58, -1, v61
	v_and_b32_e32 v53, 0x7f, v52
	v_and_b32_e32 v52, 0x7f, v58
	v_lshrrev_b32_e32 v58, 3, v52
	v_and_b32_e32 v58, 12, v58
	v_lshlrev_b32_e32 v61, 2, v52
	v_add3_u32 v65, v4, v58, v61
	v_lshrrev_b32_e32 v58, 3, v53
	v_and_b32_e32 v58, 12, v58
	v_lshlrev_b32_e32 v61, 2, v53
	v_add3_u32 v66, v4, v58, v61
	ds_read_b32 v58, v0 offset:34816
	ds_read_b32 v59, v59 offset:34816
	ds_read_b32 v60, v60 offset:34816
	ds_read_b32 v61, v62 offset:34816
	ds_read_b32 v62, v63 offset:34816
	ds_read_b32 v63, v64 offset:34816
	ds_read_b32 v64, v65 offset:34816
	ds_read_b32 v65, v66 offset:34816
	s_waitcnt lgkmcnt(8)
	global_store_dwordx4 v41, v[54:57], s[4:5] offset:16
	global_store_dwordx4 v41, v[46:49], s[10:11] offset:16
	s_waitcnt lgkmcnt(4)
	global_store_dwordx4 v41, v[58:61], s[4:5] offset:32
	global_store_dwordx4 v41, v[42:45], s[10:11] offset:32
	s_waitcnt lgkmcnt(0)
	global_store_dwordx4 v41, v[62:65], s[4:5] offset:48
	global_store_dwordx4 v41, v[50:53], s[10:11] offset:48
	s_branch .LBB0_948
